# MFMA pair order: activation fragment held across four accumulate pairs spanning both weight halves (m-major snake over the 32-MFMA block)
# speedup vs baseline: 1.0091x; 1.0091x over previous
.LBB0_169:
	s_add_u32 s34, s50, 0xfff80080
	s_addc_u32 s35, s51, -1
	s_add_i32 s52, 0, 0x10000
	s_cmp_eq_u32 s77, 28
	s_cselect_b32 s55, s36, s35
	s_cselect_b32 s54, s37, s34
	v_add_u32_e32 v145, s52, v142
	s_cselect_b32 s35, s41, s76
	s_cselect_b32 s34, s43, s71
	s_add_i32 s53, 0, 0x14000
	ds_read_b128 v[146:149], v145
	ds_read_b128 v[150:153], v145 offset:1024
	ds_read_b128 v[172:175], v145 offset:2048
	ds_read_b128 v[176:179], v145 offset:3072
	v_add_u32_e32 v145, s53, v142
	ds_read_b128 v[180:183], v145
	ds_read_b128 v[184:187], v145 offset:1024
	ds_read_b128 v[188:191], v145 offset:2048
	ds_read_b128 v[192:195], v145 offset:3072
	v_lshl_add_u64 v[154:155], s[50:51], 0, v[138:139]
	s_add_i32 m0, s57, 0xc000
	ds_read_b128 v[196:199], v144
	ds_read_b128 v[200:203], v144 offset:1024
	ds_read_b128 v[204:207], v144 offset:2048
	ds_read_b128 v[208:211], v144 offset:3072
	ds_read_b128 v[212:215], v144 offset:4096
	ds_read_b128 v[216:219], v144 offset:5120
	ds_read_b128 v[228:231], v144 offset:6144
	ds_read_b128 v[232:235], v144 offset:7168
	global_load_lds_dwordx4 v[154:155], off
	v_lshl_add_u64 v[154:155], s[50:51], 0, v[140:141]
	s_add_i32 m0, s57, 0xe000
	s_nop 0
	global_load_lds_dwordx4 v[154:155], off
	s_waitcnt vmcnt(8)
	s_waitcnt lgkmcnt(0)
	s_barrier
	s_setprio 1
	v_mfma_f32_16x16x32_bf16 v[128:131], v[146:149], v[196:199], v[128:131]
	v_mfma_f32_16x16x32_bf16 v[128:131], v[150:153], v[200:203], v[128:131]
	v_mfma_f32_16x16x32_bf16 v[124:127], v[172:175], v[196:199], v[124:127]
	v_mfma_f32_16x16x32_bf16 v[124:127], v[176:179], v[200:203], v[124:127]
	v_mfma_f32_16x16x32_bf16 v[120:123], v[180:183], v[196:199], v[120:123]
	v_mfma_f32_16x16x32_bf16 v[120:123], v[184:187], v[200:203], v[120:123]
	v_mfma_f32_16x16x32_bf16 v[116:119], v[188:191], v[196:199], v[116:119]
	v_mfma_f32_16x16x32_bf16 v[116:119], v[192:195], v[200:203], v[116:119]
	v_mfma_f32_16x16x32_bf16 v[104:107], v[180:183], v[204:207], v[104:107]
	v_mfma_f32_16x16x32_bf16 v[104:107], v[184:187], v[208:211], v[104:107]
	v_mfma_f32_16x16x32_bf16 v[100:103], v[188:191], v[204:207], v[100:103]
	v_mfma_f32_16x16x32_bf16 v[100:103], v[192:195], v[208:211], v[100:103]
	v_mfma_f32_16x16x32_bf16 v[112:115], v[146:149], v[204:207], v[112:115]
	v_mfma_f32_16x16x32_bf16 v[112:115], v[150:153], v[208:211], v[112:115]
	v_mfma_f32_16x16x32_bf16 v[108:111], v[172:175], v[204:207], v[108:111]
	v_mfma_f32_16x16x32_bf16 v[108:111], v[176:179], v[208:211], v[108:111]
	v_mfma_f32_16x16x32_bf16 v[96:99], v[146:149], v[212:215], v[96:99]
	v_mfma_f32_16x16x32_bf16 v[96:99], v[150:153], v[216:219], v[96:99]
	v_mfma_f32_16x16x32_bf16 v[92:95], v[172:175], v[212:215], v[92:95]
	v_mfma_f32_16x16x32_bf16 v[92:95], v[176:179], v[216:219], v[92:95]
	v_mfma_f32_16x16x32_bf16 v[88:91], v[180:183], v[212:215], v[88:91]
	v_mfma_f32_16x16x32_bf16 v[88:91], v[184:187], v[216:219], v[88:91]
	v_mfma_f32_16x16x32_bf16 v[84:87], v[188:191], v[212:215], v[84:87]
	v_mfma_f32_16x16x32_bf16 v[84:87], v[192:195], v[216:219], v[84:87]
	v_mfma_f32_16x16x32_bf16 v[72:75], v[180:183], v[228:231], v[72:75]
	v_mfma_f32_16x16x32_bf16 v[72:75], v[184:187], v[232:235], v[72:75]
	v_mfma_f32_16x16x32_bf16 v[68:71], v[188:191], v[228:231], v[68:71]
	v_mfma_f32_16x16x32_bf16 v[68:71], v[192:195], v[232:235], v[68:71]
	v_mfma_f32_16x16x32_bf16 v[80:83], v[146:149], v[228:231], v[80:83]
	v_mfma_f32_16x16x32_bf16 v[80:83], v[150:153], v[232:235], v[80:83]
	v_mfma_f32_16x16x32_bf16 v[76:79], v[172:175], v[228:231], v[76:79]
	v_mfma_f32_16x16x32_bf16 v[76:79], v[176:179], v[232:235], v[76:79]
	s_setprio 0
	s_barrier
	s_add_i32 s52, s52, s19
	v_lshl_add_u64 v[154:155], s[34:35], 0, v[134:135]
	s_mov_b32 m0, s52
	ds_read_b128 v[196:199], v144 offset:16384
	ds_read_b128 v[200:203], v144 offset:17408
	ds_read_b128 v[204:207], v144 offset:18432
	ds_read_b128 v[208:211], v144 offset:19456
	ds_read_b128 v[212:215], v144 offset:20480
	ds_read_b128 v[216:219], v144 offset:21504
	ds_read_b128 v[228:231], v144 offset:22528
	ds_read_b128 v[232:235], v144 offset:23552
	global_load_lds_dwordx4 v[154:155], off
	s_add_i32 m0, s52, 0x2000
	s_add_u32 s96, s34, 0x4000
	v_lshl_add_u64 v[154:155], s[34:35], 0, v[0:1]
	s_addc_u32 s97, s35, 0
	s_add_i32 s52, s53, s19
	global_load_lds_dwordx4 v[154:155], off
	v_lshl_add_u64 v[154:155], s[96:97], 0, v[134:135]
	s_mov_b32 m0, s52
	v_lshl_add_u64 v[236:237], s[54:55], 0, v[132:133]
	global_load_lds_dwordx4 v[154:155], off
	v_lshl_add_u64 v[154:155], s[96:97], 0, v[0:1]
	s_add_i32 m0, s52, 0x2000
	s_nop 0
	global_load_lds_dwordx4 v[154:155], off
	v_lshl_add_u64 v[154:155], s[54:55], 0, v[136:137]
	s_mov_b32 m0, s57
	s_nop 0
	global_load_lds_dwordx4 v[154:155], off
	s_mov_b32 m0, s58
	s_nop 0
	global_load_lds_dwordx4 v[236:237], off
	s_waitcnt vmcnt(8)
	s_waitcnt lgkmcnt(0)
	s_barrier
	s_setprio 1
	v_mfma_f32_16x16x32_bf16 v[64:67], v[146:149], v[196:199], v[64:67]
	v_mfma_f32_16x16x32_bf16 v[64:67], v[150:153], v[200:203], v[64:67]
	v_mfma_f32_16x16x32_bf16 v[60:63], v[172:175], v[196:199], v[60:63]
	v_mfma_f32_16x16x32_bf16 v[60:63], v[176:179], v[200:203], v[60:63]
	v_mfma_f32_16x16x32_bf16 v[56:59], v[180:183], v[196:199], v[56:59]
	v_mfma_f32_16x16x32_bf16 v[56:59], v[184:187], v[200:203], v[56:59]
	v_mfma_f32_16x16x32_bf16 v[52:55], v[188:191], v[196:199], v[52:55]
	v_mfma_f32_16x16x32_bf16 v[52:55], v[192:195], v[200:203], v[52:55]
	v_mfma_f32_16x16x32_bf16 v[40:43], v[180:183], v[204:207], v[40:43]
	v_mfma_f32_16x16x32_bf16 v[40:43], v[184:187], v[208:211], v[40:43]
	v_mfma_f32_16x16x32_bf16 v[36:39], v[188:191], v[204:207], v[36:39]
	v_mfma_f32_16x16x32_bf16 v[36:39], v[192:195], v[208:211], v[36:39]
	v_mfma_f32_16x16x32_bf16 v[48:51], v[146:149], v[204:207], v[48:51]
	v_mfma_f32_16x16x32_bf16 v[48:51], v[150:153], v[208:211], v[48:51]
	v_mfma_f32_16x16x32_bf16 v[44:47], v[172:175], v[204:207], v[44:47]
	v_mfma_f32_16x16x32_bf16 v[44:47], v[176:179], v[208:211], v[44:47]
	v_mfma_f32_16x16x32_bf16 v[32:35], v[146:149], v[212:215], v[32:35]
	v_mfma_f32_16x16x32_bf16 v[32:35], v[150:153], v[216:219], v[32:35]
	v_mfma_f32_16x16x32_bf16 v[28:31], v[172:175], v[212:215], v[28:31]
	v_mfma_f32_16x16x32_bf16 v[28:31], v[176:179], v[216:219], v[28:31]
	v_mfma_f32_16x16x32_bf16 v[24:27], v[180:183], v[212:215], v[24:27]
	v_mfma_f32_16x16x32_bf16 v[24:27], v[184:187], v[216:219], v[24:27]
	v_mfma_f32_16x16x32_bf16 v[20:23], v[188:191], v[212:215], v[20:23]
	v_mfma_f32_16x16x32_bf16 v[20:23], v[192:195], v[216:219], v[20:23]
	v_mfma_f32_16x16x32_bf16 v[8:11], v[180:183], v[228:231], v[8:11]
	v_mfma_f32_16x16x32_bf16 v[8:11], v[184:187], v[232:235], v[8:11]
	v_mfma_f32_16x16x32_bf16 v[4:7], v[188:191], v[228:231], v[4:7]
	v_mfma_f32_16x16x32_bf16 v[4:7], v[192:195], v[232:235], v[4:7]
	v_mfma_f32_16x16x32_bf16 v[16:19], v[146:149], v[228:231], v[16:19]
	v_mfma_f32_16x16x32_bf16 v[16:19], v[150:153], v[232:235], v[16:19]
	v_mfma_f32_16x16x32_bf16 v[12:15], v[172:175], v[228:231], v[12:15]
	v_mfma_f32_16x16x32_bf16 v[12:15], v[176:179], v[232:235], v[12:15]
	s_setprio 0
	s_barrier
	s_add_i32 s52, 0, 0x18000
	v_add_u32_e32 v145, s52, v142
	s_add_i32 s53, 0, 0x1c000
	ds_read_b128 v[146:149], v145
	ds_read_b128 v[150:153], v145 offset:1024
	ds_read_b128 v[172:175], v145 offset:2048
	ds_read_b128 v[176:179], v145 offset:3072
	v_add_u32_e32 v145, s53, v142
	ds_read_b128 v[180:183], v145
	ds_read_b128 v[184:187], v145 offset:1024
	ds_read_b128 v[188:191], v145 offset:2048
	ds_read_b128 v[192:195], v145 offset:3072
	s_add_u32 s54, s54, 0x80000
	s_addc_u32 s55, s55, 0
	s_mov_b32 m0, s59
	v_lshl_add_u64 v[238:239], s[54:55], 0, v[136:137]
	ds_read_b128 v[196:199], v144 offset:32768
	ds_read_b128 v[200:203], v144 offset:33792
	ds_read_b128 v[204:207], v144 offset:34816
	ds_read_b128 v[208:211], v144 offset:35840
	ds_read_b128 v[212:215], v144 offset:36864
	ds_read_b128 v[216:219], v144 offset:37888
	ds_read_b128 v[228:231], v144 offset:38912
	ds_read_b128 v[232:235], v144 offset:39936
	global_load_lds_dwordx4 v[238:239], off
	v_lshl_add_u64 v[238:239], s[54:55], 0, v[132:133]
	s_mov_b32 m0, s60
	s_nop 0
	global_load_lds_dwordx4 v[238:239], off
	s_waitcnt vmcnt(8)
	s_waitcnt lgkmcnt(0)
	s_barrier
	s_setprio 1
	v_mfma_f32_16x16x32_bf16 v[128:131], v[146:149], v[196:199], v[128:131]
	v_mfma_f32_16x16x32_bf16 v[128:131], v[150:153], v[200:203], v[128:131]
	v_mfma_f32_16x16x32_bf16 v[124:127], v[172:175], v[196:199], v[124:127]
	v_mfma_f32_16x16x32_bf16 v[124:127], v[176:179], v[200:203], v[124:127]
	v_mfma_f32_16x16x32_bf16 v[120:123], v[180:183], v[196:199], v[120:123]
	v_mfma_f32_16x16x32_bf16 v[120:123], v[184:187], v[200:203], v[120:123]
	v_mfma_f32_16x16x32_bf16 v[116:119], v[188:191], v[196:199], v[116:119]
	v_mfma_f32_16x16x32_bf16 v[116:119], v[192:195], v[200:203], v[116:119]
	v_mfma_f32_16x16x32_bf16 v[104:107], v[180:183], v[204:207], v[104:107]
	v_mfma_f32_16x16x32_bf16 v[104:107], v[184:187], v[208:211], v[104:107]
	v_mfma_f32_16x16x32_bf16 v[100:103], v[188:191], v[204:207], v[100:103]
	v_mfma_f32_16x16x32_bf16 v[100:103], v[192:195], v[208:211], v[100:103]
	v_mfma_f32_16x16x32_bf16 v[112:115], v[146:149], v[204:207], v[112:115]
	v_mfma_f32_16x16x32_bf16 v[112:115], v[150:153], v[208:211], v[112:115]
	v_mfma_f32_16x16x32_bf16 v[108:111], v[172:175], v[204:207], v[108:111]
	v_mfma_f32_16x16x32_bf16 v[108:111], v[176:179], v[208:211], v[108:111]
	v_mfma_f32_16x16x32_bf16 v[96:99], v[146:149], v[212:215], v[96:99]
	v_mfma_f32_16x16x32_bf16 v[96:99], v[150:153], v[216:219], v[96:99]
	v_mfma_f32_16x16x32_bf16 v[92:95], v[172:175], v[212:215], v[92:95]
	v_mfma_f32_16x16x32_bf16 v[92:95], v[176:179], v[216:219], v[92:95]
	v_mfma_f32_16x16x32_bf16 v[88:91], v[180:183], v[212:215], v[88:91]
	v_mfma_f32_16x16x32_bf16 v[88:91], v[184:187], v[216:219], v[88:91]
	v_mfma_f32_16x16x32_bf16 v[84:87], v[188:191], v[212:215], v[84:87]
	v_mfma_f32_16x16x32_bf16 v[84:87], v[192:195], v[216:219], v[84:87]
	v_mfma_f32_16x16x32_bf16 v[72:75], v[180:183], v[228:231], v[72:75]
	v_mfma_f32_16x16x32_bf16 v[72:75], v[184:187], v[232:235], v[72:75]
	v_mfma_f32_16x16x32_bf16 v[68:71], v[188:191], v[228:231], v[68:71]
	v_mfma_f32_16x16x32_bf16 v[68:71], v[192:195], v[232:235], v[68:71]
	v_mfma_f32_16x16x32_bf16 v[80:83], v[146:149], v[228:231], v[80:83]
	v_mfma_f32_16x16x32_bf16 v[80:83], v[150:153], v[232:235], v[80:83]
	v_mfma_f32_16x16x32_bf16 v[76:79], v[172:175], v[228:231], v[76:79]
	v_mfma_f32_16x16x32_bf16 v[76:79], v[176:179], v[232:235], v[76:79]
	s_setprio 0
	s_barrier
	s_add_u32 s54, s34, 0x160000
	s_addc_u32 s55, s35, 0
	s_add_i32 s52, s52, s19
	v_lshl_add_u64 v[238:239], s[54:55], 0, v[134:135]
	s_mov_b32 m0, s52
	ds_read_b128 v[196:199], v144 offset:49152
	ds_read_b128 v[200:203], v144 offset:50176
	ds_read_b128 v[204:207], v144 offset:51200
	ds_read_b128 v[208:211], v144 offset:52224
	ds_read_b128 v[212:215], v144 offset:53248
	ds_read_b128 v[216:219], v144 offset:54272
	ds_read_b128 v[228:231], v144 offset:55296
	ds_read_b128 v[232:235], v144 offset:56320
	global_load_lds_dwordx4 v[238:239], off
	s_add_i32 m0, s52, 0x2000
	s_add_u32 s34, s34, 0x164000
	v_lshl_add_u64 v[238:239], s[54:55], 0, v[0:1]
	s_addc_u32 s35, s35, 0
	s_add_i32 s52, s53, s19
	global_load_lds_dwordx4 v[238:239], off
	v_lshl_add_u64 v[238:239], s[34:35], 0, v[134:135]
	s_mov_b32 m0, s52
	v_lshl_add_u64 v[154:155], v[154:155], 0, s[14:15]
	global_load_lds_dwordx4 v[238:239], off
	v_lshl_add_u64 v[238:239], s[34:35], 0, v[0:1]
	s_add_i32 m0, s52, 0x2000
	s_nop 0
	global_load_lds_dwordx4 v[238:239], off
	s_mov_b32 m0, s61
	s_nop 0
	global_load_lds_dwordx4 v[154:155], off
	v_lshl_add_u64 v[154:155], v[236:237], 0, s[14:15]
	s_mov_b32 m0, s62
	s_nop 0
	global_load_lds_dwordx4 v[154:155], off
	s_waitcnt vmcnt(8)
	s_waitcnt lgkmcnt(0)
	s_barrier
	s_setprio 1
	v_mfma_f32_16x16x32_bf16 v[64:67], v[146:149], v[196:199], v[64:67]
	v_mfma_f32_16x16x32_bf16 v[64:67], v[150:153], v[200:203], v[64:67]
	v_mfma_f32_16x16x32_bf16 v[60:63], v[172:175], v[196:199], v[60:63]
	v_mfma_f32_16x16x32_bf16 v[60:63], v[176:179], v[200:203], v[60:63]
	v_mfma_f32_16x16x32_bf16 v[56:59], v[180:183], v[196:199], v[56:59]
	v_mfma_f32_16x16x32_bf16 v[56:59], v[184:187], v[200:203], v[56:59]
	v_mfma_f32_16x16x32_bf16 v[52:55], v[188:191], v[196:199], v[52:55]
	v_mfma_f32_16x16x32_bf16 v[52:55], v[192:195], v[200:203], v[52:55]
	v_mfma_f32_16x16x32_bf16 v[40:43], v[180:183], v[204:207], v[40:43]
	v_mfma_f32_16x16x32_bf16 v[40:43], v[184:187], v[208:211], v[40:43]
	v_mfma_f32_16x16x32_bf16 v[36:39], v[188:191], v[204:207], v[36:39]
	v_mfma_f32_16x16x32_bf16 v[36:39], v[192:195], v[208:211], v[36:39]
	v_mfma_f32_16x16x32_bf16 v[48:51], v[146:149], v[204:207], v[48:51]
	v_mfma_f32_16x16x32_bf16 v[48:51], v[150:153], v[208:211], v[48:51]
	v_mfma_f32_16x16x32_bf16 v[44:47], v[172:175], v[204:207], v[44:47]
	v_mfma_f32_16x16x32_bf16 v[44:47], v[176:179], v[208:211], v[44:47]
	v_mfma_f32_16x16x32_bf16 v[32:35], v[146:149], v[212:215], v[32:35]
	v_mfma_f32_16x16x32_bf16 v[32:35], v[150:153], v[216:219], v[32:35]
	v_mfma_f32_16x16x32_bf16 v[28:31], v[172:175], v[212:215], v[28:31]
	v_mfma_f32_16x16x32_bf16 v[28:31], v[176:179], v[216:219], v[28:31]
	v_mfma_f32_16x16x32_bf16 v[24:27], v[180:183], v[212:215], v[24:27]
	v_mfma_f32_16x16x32_bf16 v[24:27], v[184:187], v[216:219], v[24:27]
	v_mfma_f32_16x16x32_bf16 v[20:23], v[188:191], v[212:215], v[20:23]
	v_mfma_f32_16x16x32_bf16 v[20:23], v[192:195], v[216:219], v[20:23]
	v_mfma_f32_16x16x32_bf16 v[8:11], v[180:183], v[228:231], v[8:11]
	v_mfma_f32_16x16x32_bf16 v[8:11], v[184:187], v[232:235], v[8:11]
	v_mfma_f32_16x16x32_bf16 v[4:7], v[188:191], v[228:231], v[4:7]
	v_mfma_f32_16x16x32_bf16 v[4:7], v[192:195], v[232:235], v[4:7]
	v_mfma_f32_16x16x32_bf16 v[16:19], v[146:149], v[228:231], v[16:19]
	v_mfma_f32_16x16x32_bf16 v[16:19], v[150:153], v[232:235], v[16:19]
	v_mfma_f32_16x16x32_bf16 v[12:15], v[172:175], v[228:231], v[12:15]
	v_mfma_f32_16x16x32_bf16 v[12:15], v[176:179], v[232:235], v[12:15]
	s_setprio 0
	s_barrier
	s_add_i32 s77, s77, 2
	s_add_u32 s71, s71, 0x2c0000
	s_addc_u32 s76, s76, 0
	s_add_u32 s50, s50, 0x100
	s_addc_u32 s51, s51, 0
	s_cmp_gt_u32 s77, 29
	s_cbranch_scc0 .LBB0_169
	s_and_b64 vcc, exec, s[28:29]
	s_cbranch_vccz .LBB0_172
	s_barrier

.LBB0_243:
	s_add_u32 s34, s44, 0xfff80080
	s_addc_u32 s35, s45, -1
	s_add_i32 s52, 0, 0x10000
	s_cmp_eq_u32 vcc_hi, 28
	s_cselect_b32 s47, s36, s35
	s_cselect_b32 s46, s37, s34
	s_cselect_b32 s35, s55, vcc_lo
	s_cselect_b32 s34, s57, s63
	s_add_i32 s68, 0, 0x14000
	v_add_u32_e32 v144, s52, v155
	v_add_u32_e32 v180, s68, v155
	ds_read_b128 v[132:135], v144
	ds_read_b128 v[136:139], v144 offset:1024
	ds_read_b128 v[140:143], v144 offset:2048
	ds_read_b128 v[144:147], v144 offset:3072
	ds_read_b128 v[176:179], v180
	ds_read_b128 v[182:185], v180 offset:1024
	ds_read_b128 v[186:189], v180 offset:2048
	ds_read_b128 v[190:193], v180 offset:3072
	v_lshl_add_u64 v[218:219], s[44:45], 0, v[172:173]
	s_add_i32 m0, s69, 0xc000
	ds_read_b128 v[194:197], v181
	ds_read_b128 v[198:201], v181 offset:1024
	ds_read_b128 v[202:205], v181 offset:2048
	ds_read_b128 v[206:209], v181 offset:3072
	ds_read_b128 v[210:213], v181 offset:4096
	ds_read_b128 v[214:217], v181 offset:5120
	ds_read_b128 v[228:231], v181 offset:6144
	ds_read_b128 v[232:235], v181 offset:7168
	global_load_lds_dwordx4 v[218:219], off
	v_lshl_add_u64 v[218:219], s[44:45], 0, v[174:175]
	s_add_i32 m0, s69, 0xe000
	s_nop 0
	global_load_lds_dwordx4 v[218:219], off
	s_waitcnt vmcnt(8)
	s_waitcnt lgkmcnt(0)
	s_barrier
	s_setprio 1
	v_mfma_f32_16x16x32_bf16 v[128:131], v[132:135], v[194:197], v[128:131]
	v_mfma_f32_16x16x32_bf16 v[128:131], v[136:139], v[198:201], v[128:131]
	v_mfma_f32_16x16x32_bf16 v[124:127], v[140:143], v[194:197], v[124:127]
	v_mfma_f32_16x16x32_bf16 v[124:127], v[144:147], v[198:201], v[124:127]
	v_mfma_f32_16x16x32_bf16 v[120:123], v[176:179], v[194:197], v[120:123]
	v_mfma_f32_16x16x32_bf16 v[120:123], v[182:185], v[198:201], v[120:123]
	v_mfma_f32_16x16x32_bf16 v[116:119], v[186:189], v[194:197], v[116:119]
	v_mfma_f32_16x16x32_bf16 v[116:119], v[190:193], v[198:201], v[116:119]
	v_mfma_f32_16x16x32_bf16 v[104:107], v[176:179], v[202:205], v[104:107]
	v_mfma_f32_16x16x32_bf16 v[104:107], v[182:185], v[206:209], v[104:107]
	v_mfma_f32_16x16x32_bf16 v[100:103], v[186:189], v[202:205], v[100:103]
	v_mfma_f32_16x16x32_bf16 v[100:103], v[190:193], v[206:209], v[100:103]
	v_mfma_f32_16x16x32_bf16 v[112:115], v[132:135], v[202:205], v[112:115]
	v_mfma_f32_16x16x32_bf16 v[112:115], v[136:139], v[206:209], v[112:115]
	v_mfma_f32_16x16x32_bf16 v[108:111], v[140:143], v[202:205], v[108:111]
	v_mfma_f32_16x16x32_bf16 v[108:111], v[144:147], v[206:209], v[108:111]
	v_mfma_f32_16x16x32_bf16 v[96:99], v[132:135], v[210:213], v[96:99]
	v_mfma_f32_16x16x32_bf16 v[96:99], v[136:139], v[214:217], v[96:99]
	v_mfma_f32_16x16x32_bf16 v[92:95], v[140:143], v[210:213], v[92:95]
	v_mfma_f32_16x16x32_bf16 v[92:95], v[144:147], v[214:217], v[92:95]
	v_mfma_f32_16x16x32_bf16 v[88:91], v[176:179], v[210:213], v[88:91]
	v_mfma_f32_16x16x32_bf16 v[88:91], v[182:185], v[214:217], v[88:91]
	v_mfma_f32_16x16x32_bf16 v[84:87], v[186:189], v[210:213], v[84:87]
	v_mfma_f32_16x16x32_bf16 v[84:87], v[190:193], v[214:217], v[84:87]
	v_mfma_f32_16x16x32_bf16 v[72:75], v[176:179], v[228:231], v[72:75]
	v_mfma_f32_16x16x32_bf16 v[72:75], v[182:185], v[232:235], v[72:75]
	v_mfma_f32_16x16x32_bf16 v[68:71], v[186:189], v[228:231], v[68:71]
	v_mfma_f32_16x16x32_bf16 v[68:71], v[190:193], v[232:235], v[68:71]
	v_mfma_f32_16x16x32_bf16 v[80:83], v[132:135], v[228:231], v[80:83]
	v_mfma_f32_16x16x32_bf16 v[80:83], v[136:139], v[232:235], v[80:83]
	v_mfma_f32_16x16x32_bf16 v[76:79], v[140:143], v[228:231], v[76:79]
	v_mfma_f32_16x16x32_bf16 v[76:79], v[144:147], v[232:235], v[76:79]
	s_setprio 0
	s_barrier
	s_add_i32 s52, s52, s2
	v_lshl_add_u64 v[218:219], s[34:35], 0, v[150:151]
	s_mov_b32 m0, s52
	ds_read_b128 v[194:197], v181 offset:16384
	ds_read_b128 v[198:201], v181 offset:17408
	ds_read_b128 v[202:205], v181 offset:18432
	ds_read_b128 v[206:209], v181 offset:19456
	ds_read_b128 v[210:213], v181 offset:20480
	ds_read_b128 v[214:217], v181 offset:21504
	ds_read_b128 v[228:231], v181 offset:22528
	ds_read_b128 v[232:235], v181 offset:23552
	global_load_lds_dwordx4 v[218:219], off
	s_add_i32 m0, s52, 0x2000
	s_add_u32 s52, s34, 0x4000
	v_lshl_add_u64 v[218:219], s[34:35], 0, v[0:1]
	s_addc_u32 s53, s35, 0
	s_add_i32 s68, s68, s2
	global_load_lds_dwordx4 v[218:219], off
	v_lshl_add_u64 v[218:219], s[52:53], 0, v[150:151]
	s_mov_b32 m0, s68
	v_lshl_add_u64 v[236:237], s[46:47], 0, v[148:149]
	global_load_lds_dwordx4 v[218:219], off
	v_lshl_add_u64 v[218:219], s[52:53], 0, v[0:1]
	s_add_i32 m0, s68, 0x2000
	s_nop 0
	global_load_lds_dwordx4 v[218:219], off
	v_lshl_add_u64 v[218:219], s[46:47], 0, v[152:153]
	s_mov_b32 m0, s69
	s_nop 0
	global_load_lds_dwordx4 v[218:219], off
	s_mov_b32 m0, s71
	s_nop 0
	global_load_lds_dwordx4 v[236:237], off
	s_waitcnt vmcnt(8)
	s_waitcnt lgkmcnt(0)
	s_barrier
	s_setprio 1
	v_mfma_f32_16x16x32_bf16 v[64:67], v[132:135], v[194:197], v[64:67]
	v_mfma_f32_16x16x32_bf16 v[64:67], v[136:139], v[198:201], v[64:67]
	v_mfma_f32_16x16x32_bf16 v[60:63], v[140:143], v[194:197], v[60:63]
	v_mfma_f32_16x16x32_bf16 v[60:63], v[144:147], v[198:201], v[60:63]
	v_mfma_f32_16x16x32_bf16 v[56:59], v[176:179], v[194:197], v[56:59]
	v_mfma_f32_16x16x32_bf16 v[56:59], v[182:185], v[198:201], v[56:59]
	v_mfma_f32_16x16x32_bf16 v[52:55], v[186:189], v[194:197], v[52:55]
	v_mfma_f32_16x16x32_bf16 v[52:55], v[190:193], v[198:201], v[52:55]
	v_mfma_f32_16x16x32_bf16 v[40:43], v[176:179], v[202:205], v[40:43]
	v_mfma_f32_16x16x32_bf16 v[40:43], v[182:185], v[206:209], v[40:43]
	v_mfma_f32_16x16x32_bf16 v[36:39], v[186:189], v[202:205], v[36:39]
	v_mfma_f32_16x16x32_bf16 v[36:39], v[190:193], v[206:209], v[36:39]
	v_mfma_f32_16x16x32_bf16 v[48:51], v[132:135], v[202:205], v[48:51]
	v_mfma_f32_16x16x32_bf16 v[48:51], v[136:139], v[206:209], v[48:51]
	v_mfma_f32_16x16x32_bf16 v[44:47], v[140:143], v[202:205], v[44:47]
	v_mfma_f32_16x16x32_bf16 v[44:47], v[144:147], v[206:209], v[44:47]
	v_mfma_f32_16x16x32_bf16 v[32:35], v[132:135], v[210:213], v[32:35]
	v_mfma_f32_16x16x32_bf16 v[32:35], v[136:139], v[214:217], v[32:35]
	v_mfma_f32_16x16x32_bf16 v[28:31], v[140:143], v[210:213], v[28:31]
	v_mfma_f32_16x16x32_bf16 v[28:31], v[144:147], v[214:217], v[28:31]
	v_mfma_f32_16x16x32_bf16 v[24:27], v[176:179], v[210:213], v[24:27]
	v_mfma_f32_16x16x32_bf16 v[24:27], v[182:185], v[214:217], v[24:27]
	v_mfma_f32_16x16x32_bf16 v[20:23], v[186:189], v[210:213], v[20:23]
	v_mfma_f32_16x16x32_bf16 v[20:23], v[190:193], v[214:217], v[20:23]
	v_mfma_f32_16x16x32_bf16 v[8:11], v[176:179], v[228:231], v[8:11]
	v_mfma_f32_16x16x32_bf16 v[8:11], v[182:185], v[232:235], v[8:11]
	v_mfma_f32_16x16x32_bf16 v[4:7], v[186:189], v[228:231], v[4:7]
	v_mfma_f32_16x16x32_bf16 v[4:7], v[190:193], v[232:235], v[4:7]
	v_mfma_f32_16x16x32_bf16 v[16:19], v[132:135], v[228:231], v[16:19]
	v_mfma_f32_16x16x32_bf16 v[16:19], v[136:139], v[232:235], v[16:19]
	v_mfma_f32_16x16x32_bf16 v[12:15], v[140:143], v[228:231], v[12:15]
	v_mfma_f32_16x16x32_bf16 v[12:15], v[144:147], v[232:235], v[12:15]
	s_setprio 0
	s_barrier
	s_add_i32 s52, 0, 0x18000
	s_add_i32 s53, 0, 0x1c000
	v_add_u32_e32 v144, s52, v155
	v_add_u32_e32 v180, s53, v155
	ds_read_b128 v[132:135], v144
	ds_read_b128 v[136:139], v144 offset:1024
	ds_read_b128 v[140:143], v144 offset:2048
	ds_read_b128 v[144:147], v144 offset:3072
	ds_read_b128 v[176:179], v180
	ds_read_b128 v[182:185], v180 offset:1024
	ds_read_b128 v[186:189], v180 offset:2048
	ds_read_b128 v[190:193], v180 offset:3072
	s_add_u32 s46, s46, 0x80000
	s_addc_u32 s47, s47, 0
	s_mov_b32 m0, s88
	v_lshl_add_u64 v[238:239], s[46:47], 0, v[152:153]
	ds_read_b128 v[194:197], v181 offset:32768
	ds_read_b128 v[198:201], v181 offset:33792
	ds_read_b128 v[202:205], v181 offset:34816
	ds_read_b128 v[206:209], v181 offset:35840
	ds_read_b128 v[210:213], v181 offset:36864
	ds_read_b128 v[214:217], v181 offset:37888
	ds_read_b128 v[228:231], v181 offset:38912
	ds_read_b128 v[232:235], v181 offset:39936
	global_load_lds_dwordx4 v[238:239], off
	v_lshl_add_u64 v[238:239], s[46:47], 0, v[148:149]
	s_mov_b32 m0, s96
	s_nop 0
	global_load_lds_dwordx4 v[238:239], off
	s_waitcnt vmcnt(8)
	s_waitcnt lgkmcnt(0)
	s_barrier
	s_setprio 1
	v_mfma_f32_16x16x32_bf16 v[128:131], v[132:135], v[194:197], v[128:131]
	v_mfma_f32_16x16x32_bf16 v[128:131], v[136:139], v[198:201], v[128:131]
	v_mfma_f32_16x16x32_bf16 v[124:127], v[140:143], v[194:197], v[124:127]
	v_mfma_f32_16x16x32_bf16 v[124:127], v[144:147], v[198:201], v[124:127]
	v_mfma_f32_16x16x32_bf16 v[120:123], v[176:179], v[194:197], v[120:123]
	v_mfma_f32_16x16x32_bf16 v[120:123], v[182:185], v[198:201], v[120:123]
	v_mfma_f32_16x16x32_bf16 v[116:119], v[186:189], v[194:197], v[116:119]
	v_mfma_f32_16x16x32_bf16 v[116:119], v[190:193], v[198:201], v[116:119]
	v_mfma_f32_16x16x32_bf16 v[104:107], v[176:179], v[202:205], v[104:107]
	v_mfma_f32_16x16x32_bf16 v[104:107], v[182:185], v[206:209], v[104:107]
	v_mfma_f32_16x16x32_bf16 v[100:103], v[186:189], v[202:205], v[100:103]
	v_mfma_f32_16x16x32_bf16 v[100:103], v[190:193], v[206:209], v[100:103]
	v_mfma_f32_16x16x32_bf16 v[112:115], v[132:135], v[202:205], v[112:115]
	v_mfma_f32_16x16x32_bf16 v[112:115], v[136:139], v[206:209], v[112:115]
	v_mfma_f32_16x16x32_bf16 v[108:111], v[140:143], v[202:205], v[108:111]
	v_mfma_f32_16x16x32_bf16 v[108:111], v[144:147], v[206:209], v[108:111]
	v_mfma_f32_16x16x32_bf16 v[96:99], v[132:135], v[210:213], v[96:99]
	v_mfma_f32_16x16x32_bf16 v[96:99], v[136:139], v[214:217], v[96:99]
	v_mfma_f32_16x16x32_bf16 v[92:95], v[140:143], v[210:213], v[92:95]
	v_mfma_f32_16x16x32_bf16 v[92:95], v[144:147], v[214:217], v[92:95]
	v_mfma_f32_16x16x32_bf16 v[88:91], v[176:179], v[210:213], v[88:91]
	v_mfma_f32_16x16x32_bf16 v[88:91], v[182:185], v[214:217], v[88:91]
	v_mfma_f32_16x16x32_bf16 v[84:87], v[186:189], v[210:213], v[84:87]
	v_mfma_f32_16x16x32_bf16 v[84:87], v[190:193], v[214:217], v[84:87]
	v_mfma_f32_16x16x32_bf16 v[72:75], v[176:179], v[228:231], v[72:75]
	v_mfma_f32_16x16x32_bf16 v[72:75], v[182:185], v[232:235], v[72:75]
	v_mfma_f32_16x16x32_bf16 v[68:71], v[186:189], v[228:231], v[68:71]
	v_mfma_f32_16x16x32_bf16 v[68:71], v[190:193], v[232:235], v[68:71]
	v_mfma_f32_16x16x32_bf16 v[80:83], v[132:135], v[228:231], v[80:83]
	v_mfma_f32_16x16x32_bf16 v[80:83], v[136:139], v[232:235], v[80:83]
	v_mfma_f32_16x16x32_bf16 v[76:79], v[140:143], v[228:231], v[76:79]
	v_mfma_f32_16x16x32_bf16 v[76:79], v[144:147], v[232:235], v[76:79]
	s_setprio 0
	s_barrier
	s_add_u32 s46, s34, 0x70000
	s_addc_u32 s47, s35, 0
	s_add_i32 s52, s52, s2
	v_lshl_add_u64 v[238:239], s[46:47], 0, v[150:151]
	s_mov_b32 m0, s52
	ds_read_b128 v[194:197], v181 offset:49152
	ds_read_b128 v[198:201], v181 offset:50176
	ds_read_b128 v[202:205], v181 offset:51200
	ds_read_b128 v[206:209], v181 offset:52224
	ds_read_b128 v[210:213], v181 offset:53248
	ds_read_b128 v[214:217], v181 offset:54272
	ds_read_b128 v[228:231], v181 offset:55296
	ds_read_b128 v[232:235], v181 offset:56320
	global_load_lds_dwordx4 v[238:239], off
	s_add_i32 m0, s52, 0x2000
	s_add_u32 s34, s34, 0x74000
	v_lshl_add_u64 v[238:239], s[46:47], 0, v[0:1]
	s_addc_u32 s35, s35, 0
	s_add_i32 s46, s53, s2
	global_load_lds_dwordx4 v[238:239], off
	v_lshl_add_u64 v[238:239], s[34:35], 0, v[150:151]
	s_mov_b32 m0, s46
	v_lshl_add_u64 v[218:219], v[218:219], 0, s[14:15]
	global_load_lds_dwordx4 v[238:239], off
	v_lshl_add_u64 v[238:239], s[34:35], 0, v[0:1]
	s_add_i32 m0, s46, 0x2000
	s_nop 0
	global_load_lds_dwordx4 v[238:239], off
	s_mov_b32 m0, s97
	s_nop 0
	global_load_lds_dwordx4 v[218:219], off
	v_lshl_add_u64 v[218:219], v[236:237], 0, s[14:15]
	s_mov_b32 m0, s76
	s_nop 0
	global_load_lds_dwordx4 v[218:219], off
	s_waitcnt vmcnt(8)
	s_waitcnt lgkmcnt(0)
	s_barrier
	s_setprio 1
	v_mfma_f32_16x16x32_bf16 v[64:67], v[132:135], v[194:197], v[64:67]
	v_mfma_f32_16x16x32_bf16 v[64:67], v[136:139], v[198:201], v[64:67]
	v_mfma_f32_16x16x32_bf16 v[60:63], v[140:143], v[194:197], v[60:63]
	v_mfma_f32_16x16x32_bf16 v[60:63], v[144:147], v[198:201], v[60:63]
	v_mfma_f32_16x16x32_bf16 v[56:59], v[176:179], v[194:197], v[56:59]
	v_mfma_f32_16x16x32_bf16 v[56:59], v[182:185], v[198:201], v[56:59]
	v_mfma_f32_16x16x32_bf16 v[52:55], v[186:189], v[194:197], v[52:55]
	v_mfma_f32_16x16x32_bf16 v[52:55], v[190:193], v[198:201], v[52:55]
	v_mfma_f32_16x16x32_bf16 v[40:43], v[176:179], v[202:205], v[40:43]
	v_mfma_f32_16x16x32_bf16 v[40:43], v[182:185], v[206:209], v[40:43]
	v_mfma_f32_16x16x32_bf16 v[36:39], v[186:189], v[202:205], v[36:39]
	v_mfma_f32_16x16x32_bf16 v[36:39], v[190:193], v[206:209], v[36:39]
	v_mfma_f32_16x16x32_bf16 v[48:51], v[132:135], v[202:205], v[48:51]
	v_mfma_f32_16x16x32_bf16 v[48:51], v[136:139], v[206:209], v[48:51]
	v_mfma_f32_16x16x32_bf16 v[44:47], v[140:143], v[202:205], v[44:47]
	v_mfma_f32_16x16x32_bf16 v[44:47], v[144:147], v[206:209], v[44:47]
	v_mfma_f32_16x16x32_bf16 v[32:35], v[132:135], v[210:213], v[32:35]
	v_mfma_f32_16x16x32_bf16 v[32:35], v[136:139], v[214:217], v[32:35]
	v_mfma_f32_16x16x32_bf16 v[28:31], v[140:143], v[210:213], v[28:31]
	v_mfma_f32_16x16x32_bf16 v[28:31], v[144:147], v[214:217], v[28:31]
	v_mfma_f32_16x16x32_bf16 v[24:27], v[176:179], v[210:213], v[24:27]
	v_mfma_f32_16x16x32_bf16 v[24:27], v[182:185], v[214:217], v[24:27]
	v_mfma_f32_16x16x32_bf16 v[20:23], v[186:189], v[210:213], v[20:23]
	v_mfma_f32_16x16x32_bf16 v[20:23], v[190:193], v[214:217], v[20:23]
	v_mfma_f32_16x16x32_bf16 v[8:11], v[176:179], v[228:231], v[8:11]
	v_mfma_f32_16x16x32_bf16 v[8:11], v[182:185], v[232:235], v[8:11]
	v_mfma_f32_16x16x32_bf16 v[4:7], v[186:189], v[228:231], v[4:7]
	v_mfma_f32_16x16x32_bf16 v[4:7], v[190:193], v[232:235], v[4:7]
	v_mfma_f32_16x16x32_bf16 v[16:19], v[132:135], v[228:231], v[16:19]
	v_mfma_f32_16x16x32_bf16 v[16:19], v[136:139], v[232:235], v[16:19]
	v_mfma_f32_16x16x32_bf16 v[12:15], v[140:143], v[228:231], v[12:15]
	v_mfma_f32_16x16x32_bf16 v[12:15], v[144:147], v[232:235], v[12:15]
	s_setprio 0
	s_barrier
	s_add_i32 vcc_hi, vcc_hi, 2
	s_add_u32 s63, s63, 0xe0000
	s_addc_u32 vcc_lo, vcc_lo, 0
	s_add_u32 s44, s44, 0x100
	s_addc_u32 s45, s45, 0
	s_cmp_gt_u32 vcc_hi, 29
	s_cbranch_scc0 .LBB0_243
	s_and_b64 vcc, exec, s[28:29]
	s_cbranch_vccz .LBB0_246
	s_barrier

.LBB0_559:
	s_add_i32 vcc_lo, s34, 2
	s_add_u32 s35, s42, 0x80
	s_addc_u32 s52, s43, 0
	s_add_i32 s53, 0, 0x10000
	s_cmp_eq_u32 s77, s34
	s_cselect_b32 s57, s51, s52
	s_cselect_b32 s56, s50, s35
	s_cselect_b32 s35, s36, s97
	s_cselect_b32 s34, s37, s49
	s_add_i32 s68, 0, 0x14000
	v_add_u32_e32 v136, s53, v200
	v_add_u32_e32 v186, s68, v200
	ds_read_b128 v[116:119], v136
	ds_read_b128 v[120:123], v136 offset:1024
	ds_read_b128 v[124:127], v136 offset:2048
	ds_read_b128 v[136:139], v136 offset:3072
	ds_read_b128 v[148:151], v186
	ds_read_b128 v[152:155], v186 offset:1024
	ds_read_b128 v[182:185], v186 offset:2048
	ds_read_b128 v[186:189], v186 offset:3072
	v_lshl_add_u64 v[198:199], s[42:43], 0, v[178:179]
	s_add_i32 m0, s59, 0xc000
	ds_read_b128 v[190:193], v202
	ds_read_b128 v[194:197], v202 offset:1024
	ds_read_b128 v[204:207], v202 offset:2048
	ds_read_b128 v[208:211], v202 offset:3072
	ds_read_b128 v[212:215], v202 offset:4096
	ds_read_b128 v[216:219], v202 offset:5120
	ds_read_b128 v[228:231], v202 offset:6144
	ds_read_b128 v[232:235], v202 offset:7168
	global_load_lds_dwordx4 v[198:199], off
	v_lshl_add_u64 v[198:199], s[42:43], 0, v[180:181]
	s_add_i32 m0, s59, 0xe000
	s_nop 0
	global_load_lds_dwordx4 v[198:199], off
	s_waitcnt vmcnt(8)
	s_waitcnt lgkmcnt(0)
	s_barrier
	s_setprio 1
	v_mfma_f32_16x16x32_bf16 v[144:147], v[116:119], v[190:193], v[144:147]
	v_mfma_f32_16x16x32_bf16 v[144:147], v[120:123], v[194:197], v[144:147]
	v_mfma_f32_16x16x32_bf16 v[140:143], v[124:127], v[190:193], v[140:143]
	v_mfma_f32_16x16x32_bf16 v[140:143], v[136:139], v[194:197], v[140:143]
	v_mfma_f32_16x16x32_bf16 v[132:135], v[148:151], v[190:193], v[132:135]
	v_mfma_f32_16x16x32_bf16 v[132:135], v[152:155], v[194:197], v[132:135]
	v_mfma_f32_16x16x32_bf16 v[128:131], v[182:185], v[190:193], v[128:131]
	v_mfma_f32_16x16x32_bf16 v[128:131], v[186:189], v[194:197], v[128:131]
	v_mfma_f32_16x16x32_bf16 v[104:107], v[148:151], v[204:207], v[104:107]
	v_mfma_f32_16x16x32_bf16 v[104:107], v[152:155], v[208:211], v[104:107]
	v_mfma_f32_16x16x32_bf16 v[100:103], v[182:185], v[204:207], v[100:103]
	v_mfma_f32_16x16x32_bf16 v[100:103], v[186:189], v[208:211], v[100:103]
	v_mfma_f32_16x16x32_bf16 v[112:115], v[116:119], v[204:207], v[112:115]
	v_mfma_f32_16x16x32_bf16 v[112:115], v[120:123], v[208:211], v[112:115]
	v_mfma_f32_16x16x32_bf16 v[108:111], v[124:127], v[204:207], v[108:111]
	v_mfma_f32_16x16x32_bf16 v[108:111], v[136:139], v[208:211], v[108:111]
	v_mfma_f32_16x16x32_bf16 v[96:99], v[116:119], v[212:215], v[96:99]
	v_mfma_f32_16x16x32_bf16 v[96:99], v[120:123], v[216:219], v[96:99]
	v_mfma_f32_16x16x32_bf16 v[92:95], v[124:127], v[212:215], v[92:95]
	v_mfma_f32_16x16x32_bf16 v[92:95], v[136:139], v[216:219], v[92:95]
	v_mfma_f32_16x16x32_bf16 v[88:91], v[148:151], v[212:215], v[88:91]
	v_mfma_f32_16x16x32_bf16 v[88:91], v[152:155], v[216:219], v[88:91]
	v_mfma_f32_16x16x32_bf16 v[84:87], v[182:185], v[212:215], v[84:87]
	v_mfma_f32_16x16x32_bf16 v[84:87], v[186:189], v[216:219], v[84:87]
	v_mfma_f32_16x16x32_bf16 v[72:75], v[148:151], v[228:231], v[72:75]
	v_mfma_f32_16x16x32_bf16 v[72:75], v[152:155], v[232:235], v[72:75]
	v_mfma_f32_16x16x32_bf16 v[68:71], v[182:185], v[228:231], v[68:71]
	v_mfma_f32_16x16x32_bf16 v[68:71], v[186:189], v[232:235], v[68:71]
	v_mfma_f32_16x16x32_bf16 v[80:83], v[116:119], v[228:231], v[80:83]
	v_mfma_f32_16x16x32_bf16 v[80:83], v[120:123], v[232:235], v[80:83]
	v_mfma_f32_16x16x32_bf16 v[76:79], v[124:127], v[228:231], v[76:79]
	v_mfma_f32_16x16x32_bf16 v[76:79], v[136:139], v[232:235], v[76:79]
	s_setprio 0
	s_barrier
	s_add_i32 s52, s53, s58
	v_lshl_add_u64 v[198:199], s[34:35], 0, v[174:175]
	s_mov_b32 m0, s52
	ds_read_b128 v[190:193], v202 offset:16384
	ds_read_b128 v[194:197], v202 offset:17408
	ds_read_b128 v[204:207], v202 offset:18432
	ds_read_b128 v[208:211], v202 offset:19456
	ds_read_b128 v[212:215], v202 offset:20480
	ds_read_b128 v[216:219], v202 offset:21504
	ds_read_b128 v[228:231], v202 offset:22528
	ds_read_b128 v[232:235], v202 offset:23552
	global_load_lds_dwordx4 v[198:199], off
	s_add_i32 m0, s52, 0x2000
	s_add_u32 s52, s34, 0x4000
	v_lshl_add_u64 v[198:199], s[34:35], 0, v[0:1]
	s_addc_u32 s53, s35, 0
	s_add_i32 s68, s68, s58
	global_load_lds_dwordx4 v[198:199], off
	v_lshl_add_u64 v[198:199], s[52:53], 0, v[174:175]
	s_mov_b32 m0, s68
	v_lshl_add_u64 v[236:237], s[56:57], 0, v[172:173]
	global_load_lds_dwordx4 v[198:199], off
	v_lshl_add_u64 v[198:199], s[52:53], 0, v[0:1]
	s_add_i32 m0, s68, 0x2000
	s_nop 0
	global_load_lds_dwordx4 v[198:199], off
	v_lshl_add_u64 v[198:199], s[56:57], 0, v[176:177]
	s_mov_b32 m0, s59
	s_nop 0
	global_load_lds_dwordx4 v[198:199], off
	s_mov_b32 m0, s60
	s_nop 0
	global_load_lds_dwordx4 v[236:237], off
	s_waitcnt vmcnt(8)
	s_waitcnt lgkmcnt(0)
	s_barrier
	s_setprio 1
	v_mfma_f32_16x16x32_bf16 v[64:67], v[116:119], v[190:193], v[64:67]
	v_mfma_f32_16x16x32_bf16 v[64:67], v[120:123], v[194:197], v[64:67]
	v_mfma_f32_16x16x32_bf16 v[60:63], v[124:127], v[190:193], v[60:63]
	v_mfma_f32_16x16x32_bf16 v[60:63], v[136:139], v[194:197], v[60:63]
	v_mfma_f32_16x16x32_bf16 v[56:59], v[148:151], v[190:193], v[56:59]
	v_mfma_f32_16x16x32_bf16 v[56:59], v[152:155], v[194:197], v[56:59]
	v_mfma_f32_16x16x32_bf16 v[52:55], v[182:185], v[190:193], v[52:55]
	v_mfma_f32_16x16x32_bf16 v[52:55], v[186:189], v[194:197], v[52:55]
	v_mfma_f32_16x16x32_bf16 v[40:43], v[148:151], v[204:207], v[40:43]
	v_mfma_f32_16x16x32_bf16 v[40:43], v[152:155], v[208:211], v[40:43]
	v_mfma_f32_16x16x32_bf16 v[36:39], v[182:185], v[204:207], v[36:39]
	v_mfma_f32_16x16x32_bf16 v[36:39], v[186:189], v[208:211], v[36:39]
	v_mfma_f32_16x16x32_bf16 v[48:51], v[116:119], v[204:207], v[48:51]
	v_mfma_f32_16x16x32_bf16 v[48:51], v[120:123], v[208:211], v[48:51]
	v_mfma_f32_16x16x32_bf16 v[44:47], v[124:127], v[204:207], v[44:47]
	v_mfma_f32_16x16x32_bf16 v[44:47], v[136:139], v[208:211], v[44:47]
	v_mfma_f32_16x16x32_bf16 v[32:35], v[116:119], v[212:215], v[32:35]
	v_mfma_f32_16x16x32_bf16 v[32:35], v[120:123], v[216:219], v[32:35]
	v_mfma_f32_16x16x32_bf16 v[28:31], v[124:127], v[212:215], v[28:31]
	v_mfma_f32_16x16x32_bf16 v[28:31], v[136:139], v[216:219], v[28:31]
	v_mfma_f32_16x16x32_bf16 v[24:27], v[148:151], v[212:215], v[24:27]
	v_mfma_f32_16x16x32_bf16 v[24:27], v[152:155], v[216:219], v[24:27]
	v_mfma_f32_16x16x32_bf16 v[20:23], v[182:185], v[212:215], v[20:23]
	v_mfma_f32_16x16x32_bf16 v[20:23], v[186:189], v[216:219], v[20:23]
	v_mfma_f32_16x16x32_bf16 v[8:11], v[148:151], v[228:231], v[8:11]
	v_mfma_f32_16x16x32_bf16 v[8:11], v[152:155], v[232:235], v[8:11]
	v_mfma_f32_16x16x32_bf16 v[4:7], v[182:185], v[228:231], v[4:7]
	v_mfma_f32_16x16x32_bf16 v[4:7], v[186:189], v[232:235], v[4:7]
	v_mfma_f32_16x16x32_bf16 v[16:19], v[116:119], v[228:231], v[16:19]
	v_mfma_f32_16x16x32_bf16 v[16:19], v[120:123], v[232:235], v[16:19]
	v_mfma_f32_16x16x32_bf16 v[12:15], v[124:127], v[228:231], v[12:15]
	v_mfma_f32_16x16x32_bf16 v[12:15], v[136:139], v[232:235], v[12:15]
	s_setprio 0
	s_barrier
	s_add_i32 s68, 0, 0x18000
	s_add_i32 vcc_hi, 0, 0x1c000
	v_add_u32_e32 v136, s68, v200
	v_add_u32_e32 v186, vcc_hi, v200
	ds_read_b128 v[116:119], v136
	ds_read_b128 v[120:123], v136 offset:1024
	ds_read_b128 v[124:127], v136 offset:2048
	ds_read_b128 v[136:139], v136 offset:3072
	ds_read_b128 v[148:151], v186
	ds_read_b128 v[152:155], v186 offset:1024
	ds_read_b128 v[182:185], v186 offset:2048
	ds_read_b128 v[186:189], v186 offset:3072
	s_add_u32 s52, s56, s26
	s_addc_u32 s53, s57, 0
	s_mov_b32 m0, s61
	v_lshl_add_u64 v[238:239], s[52:53], 0, v[176:177]
	ds_read_b128 v[190:193], v202 offset:32768
	ds_read_b128 v[194:197], v202 offset:33792
	ds_read_b128 v[204:207], v202 offset:34816
	ds_read_b128 v[208:211], v202 offset:35840
	ds_read_b128 v[212:215], v202 offset:36864
	ds_read_b128 v[216:219], v202 offset:37888
	ds_read_b128 v[228:231], v202 offset:38912
	ds_read_b128 v[232:235], v202 offset:39936
	global_load_lds_dwordx4 v[238:239], off
	v_lshl_add_u64 v[238:239], s[52:53], 0, v[172:173]
	s_mov_b32 m0, s62
	s_nop 0
	global_load_lds_dwordx4 v[238:239], off
	s_waitcnt vmcnt(8)
	s_waitcnt lgkmcnt(0)
	s_barrier
	s_setprio 1
	v_mfma_f32_16x16x32_bf16 v[144:147], v[116:119], v[190:193], v[144:147]
	v_mfma_f32_16x16x32_bf16 v[144:147], v[120:123], v[194:197], v[144:147]
	v_mfma_f32_16x16x32_bf16 v[140:143], v[124:127], v[190:193], v[140:143]
	v_mfma_f32_16x16x32_bf16 v[140:143], v[136:139], v[194:197], v[140:143]
	v_mfma_f32_16x16x32_bf16 v[132:135], v[148:151], v[190:193], v[132:135]
	v_mfma_f32_16x16x32_bf16 v[132:135], v[152:155], v[194:197], v[132:135]
	v_mfma_f32_16x16x32_bf16 v[128:131], v[182:185], v[190:193], v[128:131]
	v_mfma_f32_16x16x32_bf16 v[128:131], v[186:189], v[194:197], v[128:131]
	v_mfma_f32_16x16x32_bf16 v[104:107], v[148:151], v[204:207], v[104:107]
	v_mfma_f32_16x16x32_bf16 v[104:107], v[152:155], v[208:211], v[104:107]
	v_mfma_f32_16x16x32_bf16 v[100:103], v[182:185], v[204:207], v[100:103]
	v_mfma_f32_16x16x32_bf16 v[100:103], v[186:189], v[208:211], v[100:103]
	v_mfma_f32_16x16x32_bf16 v[112:115], v[116:119], v[204:207], v[112:115]
	v_mfma_f32_16x16x32_bf16 v[112:115], v[120:123], v[208:211], v[112:115]
	v_mfma_f32_16x16x32_bf16 v[108:111], v[124:127], v[204:207], v[108:111]
	v_mfma_f32_16x16x32_bf16 v[108:111], v[136:139], v[208:211], v[108:111]
	v_mfma_f32_16x16x32_bf16 v[96:99], v[116:119], v[212:215], v[96:99]
	v_mfma_f32_16x16x32_bf16 v[96:99], v[120:123], v[216:219], v[96:99]
	v_mfma_f32_16x16x32_bf16 v[92:95], v[124:127], v[212:215], v[92:95]
	v_mfma_f32_16x16x32_bf16 v[92:95], v[136:139], v[216:219], v[92:95]
	v_mfma_f32_16x16x32_bf16 v[88:91], v[148:151], v[212:215], v[88:91]
	v_mfma_f32_16x16x32_bf16 v[88:91], v[152:155], v[216:219], v[88:91]
	v_mfma_f32_16x16x32_bf16 v[84:87], v[182:185], v[212:215], v[84:87]
	v_mfma_f32_16x16x32_bf16 v[84:87], v[186:189], v[216:219], v[84:87]
	v_mfma_f32_16x16x32_bf16 v[72:75], v[148:151], v[228:231], v[72:75]
	v_mfma_f32_16x16x32_bf16 v[72:75], v[152:155], v[232:235], v[72:75]
	v_mfma_f32_16x16x32_bf16 v[68:71], v[182:185], v[228:231], v[68:71]
	v_mfma_f32_16x16x32_bf16 v[68:71], v[186:189], v[232:235], v[68:71]
	v_mfma_f32_16x16x32_bf16 v[80:83], v[116:119], v[228:231], v[80:83]
	v_mfma_f32_16x16x32_bf16 v[80:83], v[120:123], v[232:235], v[80:83]
	v_mfma_f32_16x16x32_bf16 v[76:79], v[124:127], v[228:231], v[76:79]
	v_mfma_f32_16x16x32_bf16 v[76:79], v[136:139], v[232:235], v[76:79]
	s_setprio 0
	s_barrier
	s_add_u32 s52, s34, 0x40000
	s_addc_u32 s53, s35, 0
	s_add_i32 s56, s68, s58
	v_lshl_add_u64 v[238:239], s[52:53], 0, v[174:175]
	s_mov_b32 m0, s56
	ds_read_b128 v[190:193], v202 offset:49152
	ds_read_b128 v[194:197], v202 offset:50176
	ds_read_b128 v[204:207], v202 offset:51200
	ds_read_b128 v[208:211], v202 offset:52224
	ds_read_b128 v[212:215], v202 offset:53248
	ds_read_b128 v[216:219], v202 offset:54272
	ds_read_b128 v[228:231], v202 offset:55296
	ds_read_b128 v[232:235], v202 offset:56320
	global_load_lds_dwordx4 v[238:239], off
	s_add_i32 m0, s56, 0x2000
	s_add_u32 s34, s34, 0x44000
	v_lshl_add_u64 v[238:239], s[52:53], 0, v[0:1]
	s_addc_u32 s35, s35, 0
	s_add_i32 s52, vcc_hi, s58
	global_load_lds_dwordx4 v[238:239], off
	v_lshl_add_u64 v[238:239], s[34:35], 0, v[174:175]
	s_mov_b32 m0, s52
	v_lshl_add_u64 v[198:199], v[198:199], 0, s[14:15]
	global_load_lds_dwordx4 v[238:239], off
	v_lshl_add_u64 v[238:239], s[34:35], 0, v[0:1]
	s_add_i32 m0, s52, 0x2000
	s_nop 0
	global_load_lds_dwordx4 v[238:239], off
	s_mov_b32 m0, s71
	s_nop 0
	global_load_lds_dwordx4 v[198:199], off
	v_lshl_add_u64 v[198:199], v[236:237], 0, s[14:15]
	s_mov_b32 m0, s76
	s_nop 0
	global_load_lds_dwordx4 v[198:199], off
	s_waitcnt vmcnt(8)
	s_waitcnt lgkmcnt(0)
	s_barrier
	s_setprio 1
	v_mfma_f32_16x16x32_bf16 v[64:67], v[116:119], v[190:193], v[64:67]
	v_mfma_f32_16x16x32_bf16 v[64:67], v[120:123], v[194:197], v[64:67]
	v_mfma_f32_16x16x32_bf16 v[60:63], v[124:127], v[190:193], v[60:63]
	v_mfma_f32_16x16x32_bf16 v[60:63], v[136:139], v[194:197], v[60:63]
	v_mfma_f32_16x16x32_bf16 v[56:59], v[148:151], v[190:193], v[56:59]
	v_mfma_f32_16x16x32_bf16 v[56:59], v[152:155], v[194:197], v[56:59]
	v_mfma_f32_16x16x32_bf16 v[52:55], v[182:185], v[190:193], v[52:55]
	v_mfma_f32_16x16x32_bf16 v[52:55], v[186:189], v[194:197], v[52:55]
	v_mfma_f32_16x16x32_bf16 v[40:43], v[148:151], v[204:207], v[40:43]
	v_mfma_f32_16x16x32_bf16 v[40:43], v[152:155], v[208:211], v[40:43]
	v_mfma_f32_16x16x32_bf16 v[36:39], v[182:185], v[204:207], v[36:39]
	v_mfma_f32_16x16x32_bf16 v[36:39], v[186:189], v[208:211], v[36:39]
	v_mfma_f32_16x16x32_bf16 v[48:51], v[116:119], v[204:207], v[48:51]
	v_mfma_f32_16x16x32_bf16 v[48:51], v[120:123], v[208:211], v[48:51]
	v_mfma_f32_16x16x32_bf16 v[44:47], v[124:127], v[204:207], v[44:47]
	v_mfma_f32_16x16x32_bf16 v[44:47], v[136:139], v[208:211], v[44:47]
	v_mfma_f32_16x16x32_bf16 v[32:35], v[116:119], v[212:215], v[32:35]
	v_mfma_f32_16x16x32_bf16 v[32:35], v[120:123], v[216:219], v[32:35]
	v_mfma_f32_16x16x32_bf16 v[28:31], v[124:127], v[212:215], v[28:31]
	v_mfma_f32_16x16x32_bf16 v[28:31], v[136:139], v[216:219], v[28:31]
	v_mfma_f32_16x16x32_bf16 v[24:27], v[148:151], v[212:215], v[24:27]
	v_mfma_f32_16x16x32_bf16 v[24:27], v[152:155], v[216:219], v[24:27]
	v_mfma_f32_16x16x32_bf16 v[20:23], v[182:185], v[212:215], v[20:23]
	v_mfma_f32_16x16x32_bf16 v[20:23], v[186:189], v[216:219], v[20:23]
	v_mfma_f32_16x16x32_bf16 v[8:11], v[148:151], v[228:231], v[8:11]
	v_mfma_f32_16x16x32_bf16 v[8:11], v[152:155], v[232:235], v[8:11]
	v_mfma_f32_16x16x32_bf16 v[4:7], v[182:185], v[228:231], v[4:7]
	v_mfma_f32_16x16x32_bf16 v[4:7], v[186:189], v[232:235], v[4:7]
	v_mfma_f32_16x16x32_bf16 v[16:19], v[116:119], v[228:231], v[16:19]
	v_mfma_f32_16x16x32_bf16 v[16:19], v[120:123], v[232:235], v[16:19]
	v_mfma_f32_16x16x32_bf16 v[12:15], v[124:127], v[228:231], v[12:15]
	v_mfma_f32_16x16x32_bf16 v[12:15], v[136:139], v[232:235], v[12:15]
	s_setprio 0
	s_barrier
	s_add_u32 s49, s49, 0x80000
	s_addc_u32 s97, s97, 0
	s_add_u32 s42, s42, 0x100
	s_addc_u32 s43, s43, 0
	s_cmp_ge_u32 vcc_lo, s69
	s_mov_b32 s34, vcc_lo
	s_cbranch_scc0 .LBB0_559
	s_and_b64 vcc, exec, s[46:47]
	s_cbranch_vccz .LBB0_562
	s_barrier
